# nt also on ECONV row loads/stores, ERES row stores and PRO stores (all written or read exactly once per phase)
# baseline (speedup 1.0000x reference)
.LBB0_51:
	s_or_b64 exec, exec, s[38:39]
	v_add_u32_e32 v26, 2, v127
	v_ashrrev_i32_e32 v27, 31, v26
	v_lshlrev_b64 v[110:111], 11, v[26:27]
	v_lshl_add_u64 v[26:27], v[58:59], 0, v[110:111]
	global_load_dwordx4 v[102:105], v[26:27], off nt
	v_lshl_add_u64 v[26:27], v[60:61], 0, v[110:111]
	global_load_dwordx4 v[118:121], v[26:27], off nt
	v_add_u32_e32 v26, 3, v127
	v_ashrrev_i32_e32 v27, 31, v26
	v_lshlrev_b64 v[90:91], 11, v[26:27]
	v_lshl_add_u64 v[26:27], v[58:59], 0, v[90:91]
	global_load_dwordx4 v[46:49], v[26:27], off nt
	v_lshl_add_u64 v[26:27], v[60:61], 0, v[90:91]
	global_load_dwordx4 v[50:53], v[26:27], off nt
	v_add_u32_e32 v26, 4, v127
	v_ashrrev_i32_e32 v27, 31, v26
	v_lshlrev_b64 v[92:93], 11, v[26:27]
	v_lshl_add_u64 v[26:27], v[58:59], 0, v[92:93]
	v_lshl_add_u64 v[30:31], v[60:61], 0, v[92:93]
	global_load_dwordx4 v[26:29], v[26:27], off nt
	global_load_dwordx4 v[42:45], v[30:31], off nt
	v_add_u32_e32 v30, 5, v127
	v_ashrrev_i32_e32 v31, 31, v30
	v_lshlrev_b64 v[88:89], 11, v[30:31]
	v_lshl_add_u64 v[30:31], v[58:59], 0, v[88:89]
	global_load_dwordx4 v[30:33], v[30:31], off nt
	v_lshl_add_u64 v[34:35], v[60:61], 0, v[88:89]
	global_load_dwordx4 v[34:37], v[34:35], off nt
	s_waitcnt vmcnt(8)
	v_lshlrev_b32_e32 v94, 16, v54
	v_and_b32_e32 v96, 0xffff0000, v54
	v_lshlrev_b32_e32 v100, 16, v55
	v_and_b32_e32 v98, 0xffff0000, v55
	v_lshlrev_b32_e32 v54, 16, v56
	v_lshlrev_b32_e32 v106, 16, v57
	v_add_u32_e32 v126, s2, v126
	s_movk_i32 s15, 0x2003
	v_cmp_lt_i32_e32 vcc, s15, v126
	v_add_u32_e32 v127, s6, v127
	s_or_b64 s[42:43], vcc, s[42:43]
	s_waitcnt vmcnt(7)
	v_lshlrev_b32_e32 v95, 16, v102
	v_pk_mul_f32 v[124:125], v[76:77], v[94:95]
	v_and_b32_e32 v97, 0xffff0000, v102
	v_lshlrev_b32_e32 v101, 16, v103
	v_lshlrev_b32_e32 v55, 16, v104
	v_and_b32_e32 v102, 0xffff0000, v56
	v_lshlrev_b32_e32 v107, 16, v105
	v_lshlrev_b32_e32 v56, 16, v38
	s_waitcnt vmcnt(6)
	v_lshlrev_b32_e32 v0, 16, v118
	v_and_b32_e32 v94, 0xffff0000, v118
	v_lshlrev_b32_e32 v130, 16, v119
	v_pk_mul_f32 v[108:109], v[72:73], v[100:101]
	v_and_b32_e32 v100, 0xffff0000, v119
	v_lshlrev_b32_e32 v131, 16, v120
	v_pk_mul_f32 v[114:115], v[68:69], v[54:55]
	v_and_b32_e32 v54, 0xffff0000, v120
	v_lshlrev_b32_e32 v132, 16, v121
	v_pk_mul_f32 v[118:119], v[64:65], v[106:107]
	v_and_b32_e32 v106, 0xffff0000, v121
	v_lshl_add_u64 v[120:121], v[62:63], 0, v[110:111]
	v_fma_f32 v110, v22, v56, v124
	v_and_b32_e32 v99, 0xffff0000, v103
	v_and_b32_e32 v103, 0xffff0000, v104
	v_and_b32_e32 v104, 0xffff0000, v57
	s_waitcnt vmcnt(5)
	v_lshlrev_b32_e32 v57, 16, v46
	v_add_f32_e32 v110, v110, v125
	v_mul_f32_e32 v0, v110, v0
	v_pk_mul_f32 v[110:111], v[76:77], v[56:57]
	v_pk_mul_f32 v[128:129], v[78:79], v[96:97]
	v_fma_f32 v56, v22, v95, v110
	v_and_b32_e32 v110, 0xffff0000, v38
	v_fma_f32 v38, v23, v110, v128
	v_add_f32_e32 v56, v56, v111
	v_and_b32_e32 v111, 0xffff0000, v46
	v_add_f32_e32 v38, v38, v129
	v_mul_f32_e32 v38, v38, v94
	v_pk_mul_f32 v[124:125], v[78:79], v[110:111]
	v_cvt_pk_bf16_f32 v38, v0, v38
	s_waitcnt vmcnt(4)
	v_lshlrev_b32_e32 v133, 16, v50
	v_fma_f32 v0, v23, v97, v124
	v_and_b32_e32 v50, 0xffff0000, v50
	v_add_f32_e32 v0, v0, v125
	v_lshlrev_b32_e32 v124, 16, v39
	v_mul_f32_e32 v0, v0, v50
	v_lshlrev_b32_e32 v125, 16, v47
	v_fma_f32 v50, v24, v124, v108
	v_add_f32_e32 v50, v50, v109
	v_pk_mul_f32 v[108:109], v[72:73], v[124:125]
	v_lshlrev_b32_e32 v46, 16, v51
	v_fma_f32 v94, v24, v101, v108
	v_add_f32_e32 v94, v94, v109
	v_pk_mul_f32 v[112:113], v[74:75], v[98:99]
	v_mul_f32_e32 v94, v94, v46
	v_and_b32_e32 v46, 0xffff0000, v39
	v_fma_f32 v39, v25, v46, v112
	v_add_f32_e32 v39, v39, v113
	v_mul_f32_e32 v50, v50, v130
	v_and_b32_e32 v47, 0xffff0000, v47
	v_mul_f32_e32 v39, v39, v100
	v_and_b32_e32 v108, 0xffff0000, v51
	v_cvt_pk_bf16_f32 v39, v50, v39
	v_pk_mul_f32 v[50:51], v[74:75], v[46:47]
	v_lshlrev_b32_e32 v100, 16, v52
	v_fma_f32 v46, v25, v99, v50
	v_add_f32_e32 v46, v46, v51
	v_lshlrev_b32_e32 v50, 16, v40
	v_mul_f32_e32 v46, v46, v108
	v_fma_f32 v108, v18, v50, v114
	v_lshlrev_b32_e32 v51, 16, v48
	v_add_f32_e32 v108, v108, v115
	v_mul_f32_e32 v110, v108, v131
	v_pk_mul_f32 v[108:109], v[68:69], v[50:51]
	v_and_b32_e32 v52, 0xffff0000, v52
	v_fma_f32 v50, v18, v55, v108
	v_add_f32_e32 v50, v50, v109
	v_and_b32_e32 v109, 0xffff0000, v48
	v_and_b32_e32 v108, 0xffff0000, v40
	v_pk_mul_f32 v[112:113], v[70:71], v[108:109]
	v_mul_f32_e32 v50, v50, v100
	v_fma_f32 v48, v19, v103, v112
	v_add_f32_e32 v48, v48, v113
	v_lshlrev_b32_e32 v112, 16, v41
	v_lshlrev_b32_e32 v113, 16, v49
	v_pk_mul_f32 v[114:115], v[64:65], v[112:113]
	v_pk_mul_f32 v[116:117], v[70:71], v[102:103]
	v_fma_f32 v100, v20, v107, v114
	v_and_b32_e32 v105, 0xffff0000, v105
	v_mul_f32_e32 v52, v48, v52
	v_lshlrev_b32_e32 v48, 16, v53
	v_add_f32_e32 v100, v100, v115
	v_pk_mul_f32 v[122:123], v[66:67], v[104:105]
	v_fma_f32 v40, v19, v108, v116
	v_mul_f32_e32 v100, v100, v48
	v_and_b32_e32 v48, 0xffff0000, v41
	v_add_f32_e32 v40, v40, v117
	v_fma_f32 v41, v21, v48, v122
	v_mul_f32_e32 v40, v40, v54
	v_fma_f32 v54, v20, v112, v118
	v_add_f32_e32 v41, v41, v123
	v_add_f32_e32 v54, v54, v119
	v_and_b32_e32 v49, 0xffff0000, v49
	v_mul_f32_e32 v41, v41, v106
	v_cvt_pk_bf16_f32 v40, v110, v40
	v_mul_f32_e32 v54, v54, v132
	v_cvt_pk_bf16_f32 v41, v54, v41
	global_store_dwordx4 v[120:121], v[38:41], off nt
	v_and_b32_e32 v53, 0xffff0000, v53
	v_mul_f32_e32 v56, v56, v133
	v_pk_mul_f32 v[38:39], v[66:67], v[48:49]
	v_cvt_pk_bf16_f32 v40, v50, v52
	s_waitcnt vmcnt(3)
	v_lshlrev_b32_e32 v48, 16, v43
	v_fma_f32 v38, v21, v105, v38
	v_add_f32_e32 v38, v38, v39
	v_mul_f32_e32 v41, v38, v53
	v_cvt_pk_bf16_f32 v41, v100, v41
	v_lshl_add_u64 v[52:53], v[62:63], 0, v[90:91]
	v_cvt_pk_bf16_f32 v38, v56, v0
	v_cvt_pk_bf16_f32 v39, v94, v46
	global_store_dwordx4 v[52:53], v[38:41], off nt
	v_lshlrev_b32_e32 v0, 16, v42
	v_and_b32_e32 v46, 0xffff0000, v42
	v_lshlrev_b32_e32 v40, 16, v26
	s_waitcnt vmcnt(3)
	v_lshlrev_b32_e32 v41, 16, v30
	v_and_b32_e32 v50, 0xffff0000, v43
	v_pk_mov_b32 v[42:43], v[94:95], v[40:41] op_sel:[1,0]
	v_pk_mul_f32 v[40:41], v[86:87], v[40:41]
	v_pk_mul_f32 v[42:43], v[76:77], v[42:43]
	v_fma_f32 v40, v6, v57, v40
	s_waitcnt vmcnt(2)
	v_lshlrev_b32_e32 v54, 16, v34
	v_fma_f32 v42, v22, v57, v42
	v_add_f32_e32 v40, v40, v41
	v_add_f32_e32 v42, v42, v43
	v_mul_f32_e32 v54, v40, v54
	v_and_b32_e32 v41, 0xffff0000, v30
	v_and_b32_e32 v40, 0xffff0000, v26
	v_mul_f32_e32 v0, v42, v0
	v_pk_mov_b32 v[42:43], v[96:97], v[40:41] op_sel:[1,0]
	v_pk_mul_f32 v[40:41], v[14:15], v[40:41]
	v_pk_mul_f32 v[42:43], v[78:79], v[42:43]
	v_and_b32_e32 v34, 0xffff0000, v34
	v_fma_f32 v26, v23, v111, v42
	v_add_f32_e32 v26, v26, v43
	v_mul_f32_e32 v26, v26, v46
	v_cvt_pk_bf16_f32 v26, v0, v26
	v_fma_f32 v0, v7, v111, v40
	v_add_f32_e32 v0, v0, v41
	v_lshlrev_b32_e32 v40, 16, v27
	v_lshlrev_b32_e32 v41, 16, v31
	v_pk_mov_b32 v[42:43], v[100:101], v[40:41] op_sel:[1,0]
	v_mul_f32_e32 v0, v0, v34
	v_pk_mul_f32 v[42:43], v[72:73], v[42:43]
	v_pk_mul_f32 v[40:41], v[84:85], v[40:41]
	v_fma_f32 v34, v24, v125, v42
	v_add_f32_e32 v34, v34, v43
	v_mul_f32_e32 v42, v34, v48
	v_fma_f32 v34, v8, v125, v40
	v_lshlrev_b32_e32 v30, 16, v35
	v_add_f32_e32 v34, v34, v41
	v_mul_f32_e32 v40, v34, v30
	v_and_b32_e32 v31, 0xffff0000, v31
	v_and_b32_e32 v30, 0xffff0000, v27
	v_and_b32_e32 v41, 0xffff0000, v35
	v_pk_mov_b32 v[34:35], v[98:99], v[30:31] op_sel:[1,0]
	v_pk_mul_f32 v[30:31], v[16:17], v[30:31]
	v_pk_mul_f32 v[34:35], v[74:75], v[34:35]
	v_fma_f32 v30, v9, v47, v30
	v_add_f32_e32 v30, v30, v31
	v_fma_f32 v27, v25, v47, v34
	v_mul_f32_e32 v41, v30, v41
	v_lshlrev_b32_e32 v30, 16, v28
	v_lshlrev_b32_e32 v31, 16, v32
	v_add_f32_e32 v27, v27, v35
	v_pk_mov_b32 v[34:35], v[54:55], v[30:31] op_sel:[1,0]
	v_pk_mul_f32 v[30:31], v[82:83], v[30:31]
	v_mul_f32_e32 v27, v27, v50
	v_pk_mul_f32 v[34:35], v[68:69], v[34:35]
	v_fma_f32 v30, v2, v51, v30
	v_cvt_pk_bf16_f32 v27, v42, v27
	v_lshlrev_b32_e32 v42, 16, v36
	v_fma_f32 v34, v18, v51, v34
	v_add_f32_e32 v30, v30, v31
	v_lshlrev_b32_e32 v52, 16, v44
	v_add_f32_e32 v34, v34, v35
	v_mul_f32_e32 v42, v30, v42
	v_and_b32_e32 v31, 0xffff0000, v32
	v_and_b32_e32 v30, 0xffff0000, v28
	v_mul_f32_e32 v43, v34, v52
	v_pk_mov_b32 v[34:35], v[102:103], v[30:31] op_sel:[1,0]
	v_pk_mul_f32 v[30:31], v[10:11], v[30:31]
	v_and_b32_e32 v36, 0xffff0000, v36
	v_fma_f32 v30, v3, v109, v30
	v_pk_mul_f32 v[34:35], v[70:71], v[34:35]
	v_add_f32_e32 v30, v30, v31
	v_fma_f32 v28, v19, v109, v34
	v_mul_f32_e32 v36, v30, v36
	v_lshlrev_b32_e32 v30, 16, v29
	v_lshlrev_b32_e32 v31, 16, v33
	v_add_f32_e32 v28, v28, v35
	v_pk_mov_b32 v[34:35], v[106:107], v[30:31] op_sel:[1,0]
	v_pk_mul_f32 v[30:31], v[80:81], v[30:31]
	v_pk_mul_f32 v[34:35], v[64:65], v[34:35]
	v_fma_f32 v30, v4, v113, v30
	v_lshlrev_b32_e32 v32, 16, v37
	v_fma_f32 v34, v20, v113, v34
	v_add_f32_e32 v30, v30, v31
	v_add_f32_e32 v34, v34, v35
	v_mul_f32_e32 v35, v30, v32
	v_and_b32_e32 v31, 0xffff0000, v33
	v_and_b32_e32 v30, 0xffff0000, v29
	v_pk_mov_b32 v[32:33], v[104:105], v[30:31] op_sel:[1,0]
	v_and_b32_e32 v44, 0xffff0000, v44
	v_pk_mul_f32 v[32:33], v[66:67], v[32:33]
	v_lshlrev_b32_e32 v53, 16, v45
	v_fma_f32 v29, v21, v49, v32
	v_and_b32_e32 v45, 0xffff0000, v45
	v_add_f32_e32 v29, v29, v33
	v_lshl_add_u64 v[38:39], v[62:63], 0, v[92:93]
	v_mul_f32_e32 v28, v28, v44
	v_mul_f32_e32 v29, v29, v45
	v_cvt_pk_bf16_f32 v28, v43, v28
	v_mul_f32_e32 v34, v34, v53
	v_cvt_pk_bf16_f32 v29, v34, v29
	global_store_dwordx4 v[38:39], v[26:29], off nt
	v_and_b32_e32 v37, 0xffff0000, v37
	s_nop 0
	v_pk_mul_f32 v[26:27], v[12:13], v[30:31]
	v_lshl_add_u64 v[30:31], v[62:63], 0, v[88:89]
	v_fma_f32 v26, v5, v49, v26
	v_add_f32_e32 v26, v26, v27
	v_mul_f32_e32 v29, v26, v37
	v_cvt_pk_bf16_f32 v26, v54, v0
	v_cvt_pk_bf16_f32 v27, v40, v41
	v_cvt_pk_bf16_f32 v28, v42, v36
	v_cvt_pk_bf16_f32 v29, v35, v29
	global_store_dwordx4 v[30:31], v[26:29], off nt
	s_andn2_b64 exec, exec, s[42:43]
	s_cbranch_execz .LBB0_64

.LBB0_57:
	s_or_b64 exec, exec, s[38:39]
	v_cmp_lt_i32_e32 vcc, -1, v0
	v_mov_b32_e32 v38, 0
	v_mov_b32_e32 v54, 0
	v_mov_b32_e32 v55, 0
	v_mov_b32_e32 v56, 0
	v_mov_b32_e32 v57, 0
	s_and_saveexec_b64 s[38:39], vcc
	s_cbranch_execz .LBB0_59
	v_lshlrev_b64 v[28:29], 11, v[0:1]
	v_lshl_add_u64 v[28:29], v[58:59], 0, v[28:29]
	global_load_dwordx4 v[54:57], v[28:29], off nt
.LBB0_59:
	s_or_b64 exec, exec, s[38:39]
	v_cmp_lt_i32_e32 vcc, -1, v26
	v_mov_b32_e32 v39, 0
	v_mov_b32_e32 v40, 0
	v_mov_b32_e32 v41, 0
	s_and_saveexec_b64 s[38:39], vcc
	s_cbranch_execz .LBB0_51
	v_mov_b32_e32 v27, v1
	v_lshlrev_b64 v[26:27], 11, v[26:27]
	v_lshl_add_u64 v[26:27], v[58:59], 0, v[26:27]
	global_load_dwordx4 v[38:41], v[26:27], off nt
	s_branch .LBB0_51

.LBB0_119:
	s_or_b64 exec, exec, s[44:45]
	v_ashrrev_i32_e32 v19, 31, v18
	v_lshlrev_b64 v[18:19], 11, v[18:19]
	v_lshl_add_u64 v[20:21], v[60:61], 0, v[18:19]
	v_lshl_add_u64 v[18:19], v[62:63], 0, v[18:19]
	global_load_dwordx4 v[30:33], v[20:21], off nt
	global_load_dwordx4 v[26:29], v[18:19], off nt
	global_load_dwordx4 v[22:25], v[20:21], off offset:1024 nt
	s_nop 0
	global_load_dwordx4 v[18:21], v[18:19], off offset:1024 nt
	s_waitcnt vmcnt(8)
	ds_bpermute_b32 v51, v72, v50
	s_waitcnt lgkmcnt(0)
	v_add_f32_e32 v50, v50, v51
	ds_bpermute_b32 v51, v73, v50
	s_waitcnt lgkmcnt(0)
	v_add_f32_e32 v50, v50, v51
	ds_bpermute_b32 v51, v74, v50
	s_waitcnt lgkmcnt(0)
	v_add_f32_e32 v50, v50, v51
	ds_bpermute_b32 v51, v75, v50
	s_waitcnt lgkmcnt(0)
	v_add_f32_e32 v50, v50, v51
	ds_bpermute_b32 v51, v76, v50
	s_waitcnt lgkmcnt(0)
	v_add_f32_e32 v50, v50, v51
	ds_bpermute_b32 v51, v77, v50
	s_waitcnt lgkmcnt(0)
	v_add_f32_e32 v50, v50, v51
	v_fmamk_f32 v50, v50, 0x3a800000, v229
	v_cmp_gt_f32_e32 vcc, s5, v50
	v_mul_f32_e32 v51, 0x4f800000, v50
	s_nop 0
	v_cndmask_b32_e32 v50, v50, v51, vcc
	v_sqrt_f32_e32 v51, v50
	s_nop 0
	v_add_u32_e32 v52, -1, v51
	v_fma_f32 v53, -v52, v51, v50
	v_cmp_ge_f32_e64 s[44:45], 0, v53
	v_add_u32_e32 v53, 1, v51
	s_nop 0
	v_cndmask_b32_e64 v52, v51, v52, s[44:45]
	v_fma_f32 v51, -v53, v51, v50
	v_cmp_lt_f32_e64 s[44:45], 0, v51
	s_nop 1
	v_cndmask_b32_e64 v51, v52, v53, s[44:45]
	v_mul_f32_e32 v52, 0x37800000, v51
	v_cndmask_b32_e32 v51, v51, v52, vcc
	v_cmp_class_f32_e32 vcc, v50, v230
	s_mov_b64 s[44:45], -1
	s_nop 0
	v_cndmask_b32_e32 v50, v51, v50, vcc
	v_div_scale_f32 v51, s[18:19], v50, v50, 1.0
	v_rcp_f32_e32 v52, v51
	s_nop 0
	v_fma_f32 v53, -v51, v52, 1.0
	v_fmac_f32_e32 v52, v53, v52
	v_div_scale_f32 v53, vcc, 1.0, v50, 1.0
	v_mul_f32_e32 v70, v53, v52
	v_fma_f32 v71, -v51, v70, v53
	v_fmac_f32_e32 v70, v71, v52
	v_fma_f32 v51, -v51, v70, v53
	v_div_fmas_f32 v51, v51, v52, v70
	v_div_fixup_f32 v70, v51, v50, 1.0
	s_waitcnt vmcnt(5)
	v_lshlrev_b32_e32 v52, 16, v42
	v_and_b32_e32 v53, 0xffff0000, v42
	v_lshlrev_b32_e32 v42, 16, v43
	v_and_b32_e32 v43, 0xffff0000, v43
	v_lshlrev_b32_e32 v50, 16, v46
	v_and_b32_e32 v51, 0xffff0000, v46
	v_pk_mul_f32 v[52:53], v[70:71], v[52:53] op_sel_hi:[0,1]
	v_lshlrev_b32_e32 v46, 16, v47
	v_and_b32_e32 v47, 0xffff0000, v47
	v_pk_mul_f32 v[42:43], v[70:71], v[42:43] op_sel_hi:[0,1]
	v_pk_fma_f32 v[50:51], v[6:7], v[52:53], v[50:51]
	v_pk_fma_f32 v[52:53], v[8:9], v[42:43], v[46:47]
	v_lshlrev_b32_e32 v46, 16, v44
	v_and_b32_e32 v47, 0xffff0000, v44
	v_lshlrev_b32_e32 v42, 16, v48
	v_and_b32_e32 v43, 0xffff0000, v48
	v_pk_mul_f32 v[46:47], v[70:71], v[46:47] op_sel_hi:[0,1]
	v_lshlrev_b32_e32 v44, 16, v45
	v_and_b32_e32 v45, 0xffff0000, v45
	v_pk_fma_f32 v[42:43], v[14:15], v[46:47], v[42:43]
	v_lshlrev_b32_e32 v46, 16, v49
	v_and_b32_e32 v47, 0xffff0000, v49
	v_pk_mul_f32 v[44:45], v[70:71], v[44:45] op_sel_hi:[0,1]
	v_pk_fma_f32 v[44:45], v[16:17], v[44:45], v[46:47]
	s_and_b64 vcc, exec, s[26:27]
	s_cbranch_vccz .LBB0_121
	v_cvt_pk_bf16_f32 v46, v50, v51
	v_cvt_pk_bf16_f32 v47, v52, v53
	v_cvt_pk_bf16_f32 v48, v42, v43
	v_cvt_pk_bf16_f32 v49, v44, v45
	global_store_dwordx4 v[68:69], v[46:49], off nt
	v_lshlrev_b32_e32 v79, 16, v47
	v_lshlrev_b32_e32 v78, 16, v46
	v_and_b32_e32 v47, 0xffff0000, v47
	v_and_b32_e32 v46, 0xffff0000, v46
	v_pk_mul_f32 v[46:47], v[46:47], v[46:47]
	s_mov_b64 s[44:45], 0
	v_pk_fma_f32 v[46:47], v[78:79], v[78:79], v[46:47]
	v_lshlrev_b32_e32 v79, 16, v49
	v_lshlrev_b32_e32 v78, 16, v48
	v_and_b32_e32 v49, 0xffff0000, v49
	v_and_b32_e32 v48, 0xffff0000, v48
	v_pk_mul_f32 v[48:49], v[48:49], v[48:49]
	v_add_f32_e32 v46, v46, v47
	v_pk_fma_f32 v[48:49], v[78:79], v[78:79], v[48:49]
	s_nop 0
	v_add_f32_e32 v46, v46, v48
	v_add_f32_e32 v48, v46, v49

.LBB0_301:
	s_or_b64 exec, exec, s[46:47]
	s_waitcnt vmcnt(4)
	ds_bpermute_b32 v70, v63, v69
	v_ashrrev_i32_e32 v19, 31, v18
	v_lshlrev_b64 v[18:19], 11, v[18:19]
	v_lshl_add_u64 v[20:21], v[52:53], 0, v[18:19]
	v_lshl_add_u64 v[22:23], v[54:55], 0, v[18:19]
	s_waitcnt lgkmcnt(0)
	v_add_f32_e32 v69, v69, v70
	ds_bpermute_b32 v70, v64, v69
	global_load_dwordx4 v[26:29], v[20:21], off nt
	global_load_dwordx4 v[30:33], v[22:23], off nt
	s_nop 0
	global_load_dwordx4 v[18:21], v[20:21], off offset:1024 nt
	s_nop 0
	global_load_dwordx4 v[22:25], v[22:23], off offset:1024 nt
	s_waitcnt lgkmcnt(0)
	v_add_f32_e32 v69, v69, v70
	ds_bpermute_b32 v70, v65, v69
	s_waitcnt lgkmcnt(0)
	v_add_f32_e32 v69, v69, v70
	ds_bpermute_b32 v70, v66, v69
	s_waitcnt lgkmcnt(0)
	v_add_f32_e32 v69, v69, v70
	ds_bpermute_b32 v70, v67, v69
	s_waitcnt lgkmcnt(0)
	v_add_f32_e32 v69, v69, v70
	ds_bpermute_b32 v70, v68, v69
	s_waitcnt lgkmcnt(0)
	v_add_f32_e32 v69, v69, v70
	v_fmamk_f32 v69, v69, 0x3a800000, v229
	v_cmp_gt_f32_e32 vcc, s5, v69
	v_mul_f32_e32 v70, 0x4f800000, v69
	s_nop 0
	v_cndmask_b32_e32 v69, v69, v70, vcc
	v_sqrt_f32_e32 v70, v69
	s_nop 0
	v_add_u32_e32 v71, -1, v70
	v_fma_f32 v72, -v71, v70, v69
	v_cmp_ge_f32_e64 s[46:47], 0, v72
	v_add_u32_e32 v72, 1, v70
	s_nop 0
	v_cndmask_b32_e64 v71, v70, v71, s[46:47]
	v_fma_f32 v70, -v72, v70, v69
	v_cmp_lt_f32_e64 s[46:47], 0, v70
	s_nop 1
	v_cndmask_b32_e64 v70, v71, v72, s[46:47]
	v_mul_f32_e32 v71, 0x37800000, v70
	v_cndmask_b32_e32 v70, v70, v71, vcc
	v_cmp_class_f32_e32 vcc, v69, v230
	s_nop 1
	v_cndmask_b32_e32 v69, v70, v69, vcc
	v_div_scale_f32 v70, s[16:17], v69, v69, 1.0
	v_rcp_f32_e32 v71, v70
	s_nop 0
	v_fma_f32 v72, -v70, v71, 1.0
	v_fmac_f32_e32 v71, v72, v71
	v_div_scale_f32 v72, vcc, 1.0, v69, 1.0
	v_mul_f32_e32 v73, v72, v71
	v_fma_f32 v74, -v70, v73, v72
	v_fmac_f32_e32 v73, v74, v71
	v_fma_f32 v70, -v70, v73, v72
	v_div_fmas_f32 v70, v70, v71, v73
	v_div_fixup_f32 v69, v70, v69, 1.0
	s_waitcnt vmcnt(5)
	v_lshlrev_b32_e32 v71, 16, v46
	v_lshlrev_b32_e32 v70, 16, v42
	v_mul_f32_e32 v71, v69, v71
	v_and_b32_e32 v46, 0xffff0000, v46
	v_fmac_f32_e32 v70, v6, v71
	v_and_b32_e32 v42, 0xffff0000, v42
	v_mul_f32_e32 v46, v69, v46
	v_lshlrev_b32_e32 v71, 16, v47
	v_fmac_f32_e32 v42, v7, v46
	v_lshlrev_b32_e32 v46, 16, v43
	v_mul_f32_e32 v71, v69, v71
	v_and_b32_e32 v47, 0xffff0000, v47
	v_fmac_f32_e32 v46, v8, v71
	v_and_b32_e32 v43, 0xffff0000, v43
	v_mul_f32_e32 v47, v69, v47
	v_lshlrev_b32_e32 v71, 16, v48
	v_fmac_f32_e32 v43, v9, v47
	v_lshlrev_b32_e32 v47, 16, v44
	v_mul_f32_e32 v71, v69, v71
	v_and_b32_e32 v48, 0xffff0000, v48
	v_fmac_f32_e32 v47, v14, v71
	v_and_b32_e32 v44, 0xffff0000, v44
	v_mul_f32_e32 v48, v69, v48
	v_lshlrev_b32_e32 v71, 16, v49
	v_and_b32_e32 v49, 0xffff0000, v49
	v_fmac_f32_e32 v44, v15, v48
	v_lshlrev_b32_e32 v48, 16, v45
	v_and_b32_e32 v45, 0xffff0000, v45
	v_mul_f32_e32 v49, v69, v49
	v_mul_f32_e32 v71, v69, v71
	v_fmac_f32_e32 v45, v17, v49
	v_cvt_pk_bf16_f32 v42, v70, v42
	v_fmac_f32_e32 v48, v16, v71
	v_cvt_pk_bf16_f32 v43, v46, v43
	v_cvt_pk_bf16_f32 v44, v47, v44
	v_cvt_pk_bf16_f32 v45, v48, v45
	global_store_dwordx4 v[60:61], v[42:45], off nt
	v_lshlrev_b32_e32 v46, 16, v42
	s_nop 0
	v_and_b32_e32 v42, 0xffff0000, v42
	v_mul_f32_e32 v42, v42, v42
	v_fmac_f32_e32 v42, v46, v46
	v_lshlrev_b32_e32 v46, 16, v43
	v_and_b32_e32 v43, 0xffff0000, v43
	v_mul_f32_e32 v43, v43, v43
	v_fmac_f32_e32 v43, v46, v46
	v_add_f32_e32 v42, v42, v43
	v_lshlrev_b32_e32 v43, 16, v44
	v_and_b32_e32 v44, 0xffff0000, v44
	v_mul_f32_e32 v44, v44, v44
	v_fmac_f32_e32 v44, v43, v43
	v_add_f32_e32 v42, v42, v44
	v_and_b32_e32 v44, 0xffff0000, v45
	v_lshlrev_b32_e32 v43, 16, v45
	v_mul_f32_e32 v44, v44, v44
	v_fmac_f32_e32 v44, v43, v43
	v_add_f32_e32 v42, v42, v44
	s_waitcnt vmcnt(5)
	v_lshlrev_b32_e32 v44, 16, v38
	v_lshlrev_b32_e32 v43, 16, v34
	v_mul_f32_e32 v44, v69, v44
	v_and_b32_e32 v38, 0xffff0000, v38
	v_fmac_f32_e32 v43, v10, v44
	v_and_b32_e32 v34, 0xffff0000, v34
	v_mul_f32_e32 v38, v69, v38
	v_lshlrev_b32_e32 v44, 16, v39
	v_fmac_f32_e32 v34, v11, v38
	v_lshlrev_b32_e32 v38, 16, v35
	v_mul_f32_e32 v44, v69, v44
	v_and_b32_e32 v39, 0xffff0000, v39
	v_fmac_f32_e32 v38, v12, v44
	v_and_b32_e32 v35, 0xffff0000, v35
	v_mul_f32_e32 v39, v69, v39
	v_lshlrev_b32_e32 v44, 16, v40
	v_fmac_f32_e32 v35, v13, v39
	v_lshlrev_b32_e32 v39, 16, v36
	v_mul_f32_e32 v44, v69, v44
	v_and_b32_e32 v40, 0xffff0000, v40
	v_fmac_f32_e32 v39, v2, v44
	v_and_b32_e32 v36, 0xffff0000, v36
	v_mul_f32_e32 v40, v69, v40
	v_lshlrev_b32_e32 v44, 16, v41
	v_and_b32_e32 v41, 0xffff0000, v41
	v_fmac_f32_e32 v36, v3, v40
	v_lshlrev_b32_e32 v40, 16, v37
	v_and_b32_e32 v37, 0xffff0000, v37
	v_mul_f32_e32 v41, v69, v41
	v_mul_f32_e32 v44, v69, v44
	v_fmac_f32_e32 v37, v5, v41
	v_cvt_pk_bf16_f32 v34, v43, v34
	v_fmac_f32_e32 v40, v4, v44
	v_cvt_pk_bf16_f32 v35, v38, v35
	v_cvt_pk_bf16_f32 v36, v39, v36
	v_cvt_pk_bf16_f32 v37, v40, v37
	global_store_dwordx4 v[60:61], v[34:37], off offset:1024 nt
	v_lshlrev_b32_e32 v38, 16, v34
	s_nop 0
	v_and_b32_e32 v34, 0xffff0000, v34
	v_mul_f32_e32 v34, v34, v34
	v_fmac_f32_e32 v34, v38, v38
	v_lshlrev_b32_e32 v38, 16, v35
	v_and_b32_e32 v35, 0xffff0000, v35
	v_mul_f32_e32 v35, v35, v35
	v_add_f32_e32 v34, v42, v34
	v_fmac_f32_e32 v35, v38, v38
	v_add_f32_e32 v34, v34, v35
	v_lshlrev_b32_e32 v35, 16, v36
	v_and_b32_e32 v36, 0xffff0000, v36
	v_mul_f32_e32 v36, v36, v36
	v_fmac_f32_e32 v36, v35, v35
	v_add_f32_e32 v34, v34, v36
	v_and_b32_e32 v36, 0xffff0000, v37
	v_lshlrev_b32_e32 v35, 16, v37
	v_mul_f32_e32 v36, v36, v36
	v_fmac_f32_e32 v36, v35, v35
	v_add_f32_e32 v34, v34, v36
	ds_bpermute_b32 v35, v63, v34
	s_waitcnt lgkmcnt(0)
	v_add_f32_e32 v34, v34, v35
	ds_bpermute_b32 v35, v64, v34
	s_waitcnt lgkmcnt(0)
	v_add_f32_e32 v34, v34, v35
	ds_bpermute_b32 v35, v65, v34
	s_waitcnt lgkmcnt(0)
	v_add_f32_e32 v34, v34, v35
	ds_bpermute_b32 v35, v66, v34
	s_waitcnt lgkmcnt(0)
	v_add_f32_e32 v34, v34, v35
	ds_bpermute_b32 v35, v67, v34
	s_waitcnt lgkmcnt(0)
	v_add_f32_e32 v34, v34, v35
	ds_bpermute_b32 v35, v68, v34
	s_and_saveexec_b64 s[68:69], s[42:43]
	s_cbranch_execz .LBB0_303
	s_waitcnt lgkmcnt(0)
	v_add_f32_e32 v34, v34, v35
	v_fmamk_f32 v34, v34, 0x3a800000, v229
	v_mul_f32_e32 v35, 0x4f800000, v34
	v_cmp_gt_f32_e32 vcc, s5, v34
	s_nop 1
	v_cndmask_b32_e32 v34, v34, v35, vcc
	v_sqrt_f32_e32 v35, v34
	s_nop 0
	v_add_u32_e32 v36, -1, v35
	v_fma_f32 v38, -v36, v35, v34
	v_add_u32_e32 v37, 1, v35
	v_cmp_ge_f32_e64 s[46:47], 0, v38
	s_nop 1
	v_cndmask_b32_e64 v36, v35, v36, s[46:47]
	v_fma_f32 v35, -v37, v35, v34
	v_cmp_lt_f32_e64 s[46:47], 0, v35
	s_nop 1
	v_cndmask_b32_e64 v35, v36, v37, s[46:47]
	v_mul_f32_e32 v36, 0x37800000, v35
	v_cndmask_b32_e32 v35, v35, v36, vcc
	v_cmp_class_f32_e32 vcc, v34, v230
	s_nop 1
	v_cndmask_b32_e32 v34, v35, v34, vcc
	v_div_scale_f32 v35, s[16:17], v34, v34, 1.0
	v_rcp_f32_e32 v36, v35
	s_nop 0
	v_fma_f32 v37, -v35, v36, 1.0
	v_fmac_f32_e32 v36, v37, v36
	v_div_scale_f32 v37, vcc, 1.0, v34, 1.0
	v_mul_f32_e32 v38, v37, v36
	v_fma_f32 v39, -v35, v38, v37
	v_fmac_f32_e32 v38, v39, v36
	v_fma_f32 v35, -v35, v38, v37
	v_div_fmas_f32 v35, v35, v36, v38
	v_div_fixup_f32 v36, v35, v34, 1.0
	v_lshl_add_u64 v[34:35], v[58:59], 2, s[86:87]
	global_store_dword v[34:35], v36, off

.LBB0_624:
	ds_read2_b32 v[18:19], v22 offset1:65
	ds_read2_b32 v[26:27], v22 offset0:130 offset1:195
	v_add_u32_e32 v17, 0x400, v22
	ds_read2_b32 v[28:29], v17 offset0:4 offset1:69
	ds_read2_b32 v[30:31], v17 offset0:134 offset1:199
	v_mov_b32_e32 v17, v1
	s_waitcnt lgkmcnt(3)
	v_cvt_pk_bf16_f32 v24, v18, v19
	v_mad_u64_u32 v[18:19], s[36:37], s17, v14, 0
	s_waitcnt lgkmcnt(2)
	v_cvt_pk_bf16_f32 v25, v26, v27
	s_waitcnt lgkmcnt(1)
	v_cvt_pk_bf16_f32 v26, v28, v29
	v_mov_b32_e32 v28, v19
	v_mad_u64_u32 v[28:29], s[36:37], s17, v15, v[28:29]
	v_mov_b32_e32 v19, v28
	v_lshl_add_u64 v[18:19], v[18:19], 1, s[26:27]
	v_lshl_add_u64 v[18:19], v[18:19], 0, v[16:17]
	s_waitcnt lgkmcnt(0)
	v_cvt_pk_bf16_f32 v27, v30, v31
	global_store_dwordx4 v[18:19], v[24:27], off nt
	s_waitcnt lgkmcnt(0)
	s_barrier
	s_add_i32 s44, s44, s12
	s_add_i32 s20, s20, s12
	s_add_i32 s21, s21, s22
	s_add_i32 s23, s23, s29
	s_cmpk_lt_i32 s44, 0x2900
	s_mov_b64 s[26:27], s[30:31]
	s_mov_b32 s17, s45
	s_cbranch_scc0 .LBB0_645

.LBB0_669:
	s_or_b64 exec, exec, s[44:45]
	s_waitcnt vmcnt(0)
	v_cvt_pk_bf16_f32 v26, v26, v27
	v_cvt_pk_bf16_f32 v27, v28, v29
	v_cvt_pk_bf16_f32 v30, v30, v31
	v_cvt_pk_bf16_f32 v31, v32, v33
	v_cvt_pk_bf16_f32 v32, v22, v23
	v_cvt_pk_bf16_f32 v33, v24, v25
	s_nop 0
	v_and_b32_e32 v28, 0xffff0000, v26
	v_lshlrev_b32_e32 v0, 16, v26
	v_and_b32_e32 v35, 0xffff0000, v27
	v_mul_f32_e32 v28, v28, v28
	v_lshlrev_b32_e32 v29, 16, v27
	v_fmac_f32_e32 v28, v0, v0
	v_mul_f32_e32 v0, v35, v35
	v_fmac_f32_e32 v0, v29, v29
	v_add_f32_e32 v0, v28, v0
	v_cvt_pk_bf16_f32 v28, v14, v15
	v_cvt_pk_bf16_f32 v29, v16, v17
	s_nop 0
	v_and_b32_e32 v15, 0xffff0000, v28
	v_lshlrev_b32_e32 v14, 16, v28
	v_and_b32_e32 v17, 0xffff0000, v29
	v_mul_f32_e32 v15, v15, v15
	v_lshlrev_b32_e32 v16, 16, v29
	v_fmac_f32_e32 v15, v14, v14
	v_mul_f32_e32 v14, v17, v17
	v_fmac_f32_e32 v14, v16, v16
	v_add_f32_e32 v14, v15, v14
	v_and_b32_e32 v15, 0xffff0000, v30
	v_add_f32_e32 v0, v0, v14
	v_lshlrev_b32_e32 v14, 16, v30
	v_and_b32_e32 v17, 0xffff0000, v31
	v_mul_f32_e32 v15, v15, v15
	v_lshlrev_b32_e32 v16, 16, v31
	v_fmac_f32_e32 v15, v14, v14
	v_mul_f32_e32 v14, v17, v17
	v_fmac_f32_e32 v14, v16, v16
	v_add_f32_e32 v14, v15, v14
	v_and_b32_e32 v15, 0xffff0000, v32
	v_add_f32_e32 v0, v0, v14
	v_lshlrev_b32_e32 v14, 16, v32
	v_and_b32_e32 v17, 0xffff0000, v33
	v_mul_f32_e32 v15, v15, v15
	v_lshlrev_b32_e32 v16, 16, v33
	v_fmac_f32_e32 v15, v14, v14
	v_mul_f32_e32 v14, v17, v17
	v_fmac_f32_e32 v14, v16, v16
	v_add_f32_e32 v14, v15, v14
	v_add_f32_e32 v14, v0, v14
	v_and_b32_e32 v0, 64, v231
	v_add_u32_e32 v24, 64, v0
	v_xor_b32_e32 v0, 32, v231
	v_cmp_lt_i32_e32 vcc, v0, v24
	s_nop 1
	v_cndmask_b32_e32 v0, v231, v0, vcc
	v_lshlrev_b32_e32 v0, 2, v0
	ds_bpermute_b32 v15, v0, v14
	s_waitcnt lgkmcnt(0)
	v_add_f32_e32 v15, v14, v15
	v_xor_b32_e32 v14, 16, v231
	v_cmp_lt_i32_e32 vcc, v14, v24
	s_nop 1
	v_cndmask_b32_e32 v14, v231, v14, vcc
	v_lshlrev_b32_e32 v14, 2, v14
	ds_bpermute_b32 v16, v14, v15
	s_waitcnt lgkmcnt(0)
	v_add_f32_e32 v16, v15, v16
	v_xor_b32_e32 v15, 8, v231
	v_cmp_lt_i32_e32 vcc, v15, v24
	s_nop 1
	v_cndmask_b32_e32 v15, v231, v15, vcc
	v_lshlrev_b32_e32 v15, 2, v15
	ds_bpermute_b32 v17, v15, v16
	s_waitcnt lgkmcnt(0)
	v_add_f32_e32 v17, v16, v17
	v_xor_b32_e32 v16, 4, v231
	v_cmp_lt_i32_e32 vcc, v16, v24
	s_nop 1
	v_cndmask_b32_e32 v16, v231, v16, vcc
	v_lshlrev_b32_e32 v16, 2, v16
	ds_bpermute_b32 v22, v16, v17
	s_waitcnt lgkmcnt(0)
	v_add_f32_e32 v25, v17, v22
	v_xor_b32_e32 v17, 2, v231
	v_cmp_lt_i32_e32 vcc, v17, v24
	v_lshlrev_b64 v[22:23], 11, v[38:39]
	v_lshl_add_u64 v[42:43], v[36:37], 0, v[22:23]
	v_cndmask_b32_e32 v17, v231, v17, vcc
	v_lshlrev_b32_e32 v17, 2, v17
	ds_bpermute_b32 v35, v17, v25
	v_xor_b32_e32 v22, 1, v231
	v_cmp_lt_i32_e32 vcc, v22, v24
	global_store_dwordx2 v[42:43], v[26:27], off nt
	global_store_dwordx2 v[42:43], v[28:29], off offset:512 nt
	global_store_dwordx2 v[42:43], v[30:31], off offset:1024 nt
	global_store_dwordx2 v[42:43], v[32:33], off offset:1536 nt
	v_cndmask_b32_e32 v22, v231, v22, vcc
	s_waitcnt lgkmcnt(0)
	v_add_f32_e32 v23, v25, v35
	v_lshlrev_b32_e32 v22, 2, v22
	ds_bpermute_b32 v24, v22, v23
	s_and_saveexec_b64 s[44:45], s[38:39]
	s_cbranch_execz .LBB0_671
	s_waitcnt lgkmcnt(0)
	v_add_f32_e32 v23, v23, v24
	v_fmamk_f32 v23, v23, 0x3a800000, v229
	v_mul_f32_e32 v24, 0x4f800000, v23
	v_cmp_gt_f32_e32 vcc, s5, v23
	s_nop 1
	v_cndmask_b32_e32 v23, v23, v24, vcc
	v_sqrt_f32_e32 v24, v23
	s_nop 0
	v_add_u32_e32 v25, -1, v24
	v_fma_f32 v27, -v25, v24, v23
	v_add_u32_e32 v26, 1, v24
	v_cmp_ge_f32_e64 s[42:43], 0, v27
	s_nop 1
	v_cndmask_b32_e64 v25, v24, v25, s[42:43]
	v_fma_f32 v24, -v26, v24, v23
	v_cmp_lt_f32_e64 s[42:43], 0, v24
	s_nop 1
	v_cndmask_b32_e64 v24, v25, v26, s[42:43]
	v_mul_f32_e32 v25, 0x37800000, v24
	v_cndmask_b32_e32 v24, v24, v25, vcc
	v_cmp_class_f32_e32 vcc, v23, v230
	s_nop 1
	v_cndmask_b32_e32 v23, v24, v23, vcc
	v_div_scale_f32 v24, s[14:15], v23, v23, 1.0
	v_rcp_f32_e32 v25, v24
	s_nop 0
	v_fma_f32 v26, -v24, v25, 1.0
	v_fmac_f32_e32 v25, v26, v25
	v_div_scale_f32 v26, vcc, 1.0, v23, 1.0
	v_mul_f32_e32 v27, v26, v25
	v_fma_f32 v28, -v24, v27, v26
	v_fmac_f32_e32 v27, v28, v25
	v_fma_f32 v24, -v24, v27, v26
	v_div_fmas_f32 v24, v24, v25, v27
	v_div_fixup_f32 v23, v24, v23, 1.0
	v_lshl_add_u64 v[24:25], v[38:39], 2, s[30:31]
	global_store_dword v[24:25], v23, off
.LBB0_671:
	s_or_b64 exec, exec, s[44:45]
	s_and_saveexec_b64 s[42:43], s[40:41]
	s_cbranch_execz .LBB0_648
	v_cvt_pk_bf16_f32 v10, v10, v11
	v_cvt_pk_bf16_f32 v11, v12, v13
	v_cvt_pk_bf16_f32 v6, v6, v7
	v_cvt_pk_bf16_f32 v7, v8, v9
	s_nop 0
	v_and_b32_e32 v13, 0xffff0000, v10
	v_lshlrev_b32_e32 v12, 16, v10
	s_waitcnt lgkmcnt(0)
	v_and_b32_e32 v24, 0xffff0000, v11
	v_mul_f32_e32 v13, v13, v13
	v_lshlrev_b32_e32 v23, 16, v11
	v_fmac_f32_e32 v13, v12, v12
	v_mul_f32_e32 v12, v24, v24
	v_fmac_f32_e32 v12, v23, v23
	v_add_f32_e32 v23, v13, v12
	v_cvt_pk_bf16_f32 v12, v2, v3
	v_cvt_pk_bf16_f32 v13, v4, v5
	v_and_b32_e32 v8, 0xffff0000, v6
	v_and_b32_e32 v3, 0xffff0000, v12
	v_lshlrev_b32_e32 v2, 16, v12
	v_and_b32_e32 v5, 0xffff0000, v13
	v_mul_f32_e32 v3, v3, v3
	v_lshlrev_b32_e32 v4, 16, v13
	v_fmac_f32_e32 v3, v2, v2
	v_mul_f32_e32 v2, v5, v5
	v_fmac_f32_e32 v2, v4, v4
	v_cvt_pk_bf16_f32 v4, v18, v19
	v_add_f32_e32 v2, v3, v2
	v_and_b32_e32 v18, 0xffff0000, v4
	v_cvt_pk_bf16_f32 v5, v20, v21
	v_lshlrev_b32_e32 v3, 16, v4
	v_and_b32_e32 v20, 0xffff0000, v5
	v_mul_f32_e32 v18, v18, v18
	v_lshlrev_b32_e32 v19, 16, v5
	v_fmac_f32_e32 v18, v3, v3
	v_mul_f32_e32 v3, v20, v20
	v_fmac_f32_e32 v3, v19, v19
	v_add_f32_e32 v2, v23, v2
	v_add_f32_e32 v3, v18, v3
	v_add_f32_e32 v2, v2, v3
	v_lshlrev_b32_e32 v3, 16, v6
	v_and_b32_e32 v18, 0xffff0000, v7
	v_mul_f32_e32 v8, v8, v8
	v_lshlrev_b32_e32 v9, 16, v7
	v_fmac_f32_e32 v8, v3, v3
	v_mul_f32_e32 v3, v18, v18
	v_fmac_f32_e32 v3, v9, v9
	v_add_f32_e32 v3, v8, v3
	v_add_f32_e32 v2, v2, v3
	ds_bpermute_b32 v0, v0, v2
	s_waitcnt lgkmcnt(0)
	v_add_f32_e32 v0, v2, v0
	ds_bpermute_b32 v2, v14, v0
	s_waitcnt lgkmcnt(0)
	v_add_f32_e32 v0, v0, v2
	ds_bpermute_b32 v2, v15, v0
	s_waitcnt lgkmcnt(0)
	v_add_f32_e32 v0, v0, v2
	ds_bpermute_b32 v2, v16, v0
	s_waitcnt lgkmcnt(0)
	v_add_f32_e32 v0, v0, v2
	ds_bpermute_b32 v14, v17, v0
	v_lshlrev_b64 v[2:3], 11, v[40:41]
	v_lshl_add_u64 v[8:9], v[36:37], 0, v[2:3]
	global_store_dwordx2 v[8:9], v[10:11], off nt
	global_store_dwordx2 v[8:9], v[12:13], off offset:512 nt
	global_store_dwordx2 v[8:9], v[4:5], off offset:1024 nt
	global_store_dwordx2 v[8:9], v[6:7], off offset:1536 nt
	s_waitcnt lgkmcnt(0)
	v_add_f32_e32 v0, v0, v14
	ds_bpermute_b32 v2, v22, v0
	s_and_b64 exec, exec, s[38:39]
	s_cbranch_execz .LBB0_648
	s_waitcnt lgkmcnt(0)
	v_add_f32_e32 v0, v0, v2
	v_fmamk_f32 v0, v0, 0x3a800000, v229
	v_mul_f32_e32 v2, 0x4f800000, v0
	v_cmp_gt_f32_e32 vcc, s5, v0
	s_nop 1
	v_cndmask_b32_e32 v0, v0, v2, vcc
	v_sqrt_f32_e32 v2, v0
	s_nop 0
	v_add_u32_e32 v3, -1, v2
	v_fma_f32 v5, -v3, v2, v0
	v_add_u32_e32 v4, 1, v2
	v_cmp_ge_f32_e64 s[40:41], 0, v5
	s_nop 1
	v_cndmask_b32_e64 v3, v2, v3, s[40:41]
	v_fma_f32 v2, -v4, v2, v0
	v_cmp_lt_f32_e64 s[40:41], 0, v2
	s_nop 1
	v_cndmask_b32_e64 v2, v3, v4, s[40:41]
	v_mul_f32_e32 v3, 0x37800000, v2
	v_cndmask_b32_e32 v2, v2, v3, vcc
	v_cmp_class_f32_e32 vcc, v0, v230
	s_nop 1
	v_cndmask_b32_e32 v0, v2, v0, vcc
	v_div_scale_f32 v2, s[14:15], v0, v0, 1.0
	v_rcp_f32_e32 v3, v2
	s_nop 0
	v_fma_f32 v4, -v2, v3, 1.0
	v_fmac_f32_e32 v3, v4, v3
	v_div_scale_f32 v4, vcc, 1.0, v0, 1.0
	v_mul_f32_e32 v5, v4, v3
	v_fma_f32 v6, -v2, v5, v4
	v_fmac_f32_e32 v5, v6, v3
	v_fma_f32 v2, -v2, v5, v4
	v_div_fmas_f32 v2, v2, v3, v5
	v_div_fixup_f32 v0, v2, v0, 1.0
	v_lshl_add_u64 v[2:3], v[40:41], 2, s[30:31]
	global_store_dword v[2:3], v0, off
	s_branch .LBB0_648
